# attn0 sample part: K tiles stored fragment-major and V^T tiles tile-major (producers in prep0 changed together) so each tile load touches 8-16 lines instead of 32-64
# speedup vs baseline: 1.0652x; 1.0154x over previous
.LBB0_585:
	s_andn2_b64 vcc, exec, s[0:1]
	s_cbranch_vccnz .LBB0_692
	v_mov_b32_e32 v2, v0
	v_mov_b32_e32 v4, v0
	s_mov_b32 s0, s87
	v_mov_b32_e32 v1, v0
	s_nop 0
	v_ashrrev_i32_e32 v1, 8, v1
	v_lshl_add_u32 v1, s0, 1, v1
	s_movk_i32 s0, 0x400
	v_cmp_gt_i32_e32 vcc, s0, v1
	s_and_saveexec_b64 s[6:7], vcc
	v_readlane_b32 s18, v254, 24
	v_readlane_b32 s40, v254, 18
	v_readlane_b32 s19, v254, 25
	v_readlane_b32 s41, v254, 19
	s_cbranch_execz .LBB0_691
	v_lshrrev_b32_e32 v9, 1, v4
	v_and_b32_e32 v154, 31, v4
	v_and_b32_e32 v163, 32, v9
	s_load_dword s0, s[20:21], 0x0
	v_lshlrev_b32_e32 v2, 8, v2
	v_bfe_u32 v8, v4, 5, 1
	v_or_b32_e32 v165, v163, v154
	v_and_b32_e32 v5, 0xffff0000, v2
	v_and_b32_e32 v150, 0xff, v4
	v_lshlrev_b32_e32 v2, 7, v154
	v_lshlrev_b32_e32 v156, 3, v8
	v_bfe_u32 v157, v4, 7, 1
	v_sub_u32_e64 v4, v165, 8 clamp
	v_lshl_add_u64 v[6:7], s[36:37], 0, v[2:3]
	v_lshlrev_b32_e32 v2, 4, v8
	v_min_u32_e32 v167, 48, v4
	v_lshl_or_b32 v4, v154, 8, v156
	v_add_u32_e32 v151, 0, v5
	v_lshl_add_u64 v[152:153], v[6:7], 0, v[2:3]
	v_lshl_or_b32 v162, v154, 6, v156
	v_lshl_or_b32 v2, v154, 13, v156
	v_lshlrev_b32_e32 v6, 10, v154
	v_lshlrev_b32_e32 v174, 2, v8
	v_or_b32_e32 v8, 0x2000, v4
	v_lshl_or_b32 v5, v150, 2, v5
	v_and_b32_e32 v155, 0x60, v9
	v_or_b32_e32 v164, 16, v162
	v_or_b32_e32 v166, 32, v162
	v_or_b32_e32 v168, 48, v162
	v_or_b32_e32 v170, 0x40000, v2
	v_or_b32_e32 v172, 0x40010, v2
	v_add_u32_e32 v169, 16, v167
	s_waitcnt lgkmcnt(0)
	s_lshl_b32 s2, s0, 1
	v_or_b32_e32 v171, 1, v174
	v_or_b32_e32 v173, 2, v174
	v_or_b32_e32 v175, 3, v174
	v_or_b32_e32 v204, 8, v174
	v_or_b32_e32 v205, 9, v174
	v_or_b32_e32 v206, 10, v174
	v_or_b32_e32 v207, 11, v174
	v_or_b32_e32 v208, 17, v174
	v_or_b32_e32 v209, 18, v174
	v_or_b32_e32 v210, 19, v174
	v_or_b32_e32 v211, 24, v174
	v_or_b32_e32 v212, 25, v174
	v_or_b32_e32 v213, 26, v174
	v_or_b32_e32 v214, 27, v174
	v_or_b32_e32 v215, 0xffffff00, v150
	v_add_u32_e32 v216, 0, v5
	s_mov_b64 s[8:9], 0
	v_lshlrev_b32_e32 v176, 1, v2
	v_lshlrev_b32_e32 v178, 1, v156
	v_lshl_or_b32 v178, v154, 6, v178
	v_add_u32_e32 v180, 0x800, v178
	v_lshlrev_b32_e32 v182, 1, v6
	v_lshlrev_b32_e32 v184, 1, v174
	s_branch .LBB0_590

.LBB0_610:
	s_andn2_saveexec_b64 s[10:11], s[0:1]
	s_cbranch_execz .LBB0_589
	v_lshlrev_b32_e32 v2, 1, v156
	v_lshl_or_b32 v2, v154, 5, v2
	s_waitcnt vmcnt(0) lgkmcnt(0)
	s_barrier
	s_load_dwordx2 s[0:1], s[30:31], 0xb8
	v_bfe_u32 v183, v1, 4, 4
	s_nop 5
	v_mul_u32_u24_e32 v4, 0x1d1, v183
	v_add_lshl_u32 v4, v150, v4, 2
	v_mov_b32_e32 v5, v3
	s_waitcnt lgkmcnt(0)
	v_lshl_add_u64 v[4:5], s[0:1], 0, v[4:5]
	s_mov_b64 s[0:1], 0
	v_mov_b32_e32 v6, v216
	v_mov_b32_e32 v7, v215
	s_movk_i32 s3, 0xd0
.LBB0_612:
	global_load_dword v8, v[4:5], off
	v_add_u32_e32 v7, 0x100, v7
	s_mov_b64 s[4:5], 0x400
	v_cmp_lt_u32_e32 vcc, s3, v7
	v_lshl_add_u64 v[4:5], v[4:5], 0, s[4:5]
	s_or_b64 s[0:1], vcc, s[0:1]
	s_waitcnt vmcnt(0)
	v_mul_f32_e32 v8, 0x3fb8aa3b, v8
	ds_write_b32 v6, v8
	v_add_u32_e32 v6, 0x400, v6
	s_andn2_b64 exec, exec, s[0:1]
	s_cbranch_execnz .LBB0_612
	s_or_b64 exec, exec, s[0:1]
	v_lshlrev_b32_e32 v4, 1, v1
	v_ashrrev_i32_e32 v5, 8, v1
	v_and_or_b32 v12, v4, 30, v157
	v_lshlrev_b32_e32 v4, 11, v5
	v_lshlrev_b32_e32 v6, 6, v12
	v_or3_b32 v6, v4, v6, v163
	v_add_u32_e32 v186, 0x1000, v6
	v_lshl_or_b32 v6, v5, 4, v183
	v_ashrrev_i32_e32 v7, 31, v6
	v_lshlrev_b64 v[6:7], 15, v[6:7]
	v_lshl_add_u64 v[122:123], s[52:53], 0, v[6:7]
	v_lshl_add_u64 v[124:125], s[18:19], 0, v[6:7]
	v_lshlrev_b32_e32 v6, 13, v183
	v_mov_b32_e32 v7, v3
	v_ashrrev_i32_e32 v187, 31, v186
	v_lshl_add_u64 v[8:9], v[6:7], 0, v[186:187]
	v_lshlrev_b64 v[8:9], 7, v[8:9]
	v_lshl_add_u64 v[8:9], v[152:153], 0, v[8:9]
	s_waitcnt lgkmcnt(0)
	s_barrier
	global_load_dwordx4 v[54:57], v[8:9], off
	global_load_dwordx4 v[58:61], v[8:9], off offset:32
	global_load_dwordx4 v[62:65], v[8:9], off offset:64
	global_load_dwordx4 v[66:69], v[8:9], off offset:96
	v_lshl_add_u64 v[8:9], v[122:123], 0, v[2:3]
	v_mov_b32_e32 v179, v3
	global_load_dwordx4 v[106:109], v[8:9], off
	global_load_dwordx4 v[102:105], v[8:9], off offset:1024
	global_load_dwordx4 v[110:113], v[8:9], off offset:2048
	global_load_dwordx4 v[118:121], v[8:9], off offset:3072
	v_lshl_add_u64 v[8:9], v[124:125], 0, v[178:179]
	v_mov_b32_e32 v181, v3
	v_lshl_add_u64 v[10:11], v[124:125], 0, v[180:181]
	global_load_dwordx4 v[82:85], v[8:9], off
	global_load_dwordx4 v[70:73], v[8:9], off offset:32
	global_load_dwordx4 v[78:81], v[10:11], off
	global_load_dwordx4 v[74:77], v[10:11], off offset:32
	v_max_i32_e32 v5, 4, v12
	v_add_u32_e32 v5, -4, v5
	v_min_u32_e32 v130, 24, v5
	v_ashrrev_i32_e32 v5, 31, v4
	v_lshl_add_u64 v[6:7], v[4:5], 0, v[6:7]
	v_lshlrev_b64 v[6:7], 7, v[6:7]
	v_lshl_add_u64 v[6:7], s[38:39], 0, v[6:7]
	s_mov_b64 s[0:1], 0x80000
	v_lshl_add_u64 v[126:127], v[6:7], 0, s[0:1]
	v_lshlrev_b32_e32 v6, 20, v183
	v_mov_b32_e32 v7, v3
	v_lshl_add_u64 v[6:7], s[54:55], 0, v[6:7]
	v_lshlrev_b32_e32 v4, 8, v4
	v_lshl_add_u64 v[4:5], v[4:5], 0, v[6:7]
	s_mov_b64 s[0:1], 0x2000
	v_lshl_add_u64 v[128:129], v[4:5], 0, s[0:1]
	v_sub_u32_e32 v131, v130, v12
	s_mov_b32 s3, 0
	v_mov_b32_e32 v20, v3
	v_mov_b32_e32 v21, v3
	v_mov_b32_e32 v22, v3
	v_mov_b32_e32 v23, v3
	v_mov_b32_e32 v24, v3
	v_mov_b32_e32 v25, v3
	v_mov_b32_e32 v26, v3
	v_mov_b32_e32 v27, v3
	v_mov_b32_e32 v28, v3
	v_mov_b32_e32 v29, v3
	v_mov_b32_e32 v30, v3
	v_mov_b32_e32 v31, v3
	v_mov_b32_e32 v32, v3
	v_mov_b32_e32 v33, v3
	v_mov_b32_e32 v34, v3
	v_mov_b32_e32 v35, v3
	v_mov_b32_e32 v4, v3
	v_mov_b32_e32 v5, v3
	v_mov_b32_e32 v6, v3
	v_mov_b32_e32 v7, v3
	v_mov_b32_e32 v8, v3
	v_mov_b32_e32 v9, v3
	v_mov_b32_e32 v10, v3
	v_mov_b32_e32 v11, v3
	v_mov_b32_e32 v12, v3
	v_mov_b32_e32 v13, v3
	v_mov_b32_e32 v14, v3
	v_mov_b32_e32 v15, v3
	v_mov_b32_e32 v16, v3
	v_mov_b32_e32 v17, v3
	v_mov_b32_e32 v18, v3
	v_mov_b32_e32 v19, v3
	v_mov_b32_e32 v37, 0
	s_mov_b32 s12, -8
	v_mov_b32_e32 v132, 0

.LBB0_618:
	v_lshl_add_u64 v[38:39], v[38:39], 0, v[2:3]
	global_load_dwordx4 v[98:101], v[38:39], off
	global_load_dwordx4 v[94:97], v[38:39], off offset:1024
	global_load_dwordx4 v[90:93], v[38:39], off offset:2048
	global_load_dwordx4 v[86:89], v[38:39], off offset:3072
	s_mov_b64 s[4:5], -1
	s_and_b64 vcc, exec, s[0:1]
	s_cbranch_vccz .LBB0_620
	s_add_i32 s0, s13, -8
	s_lshr_b32 s0, s0, 1
	v_add_u32_e32 v38, s0, v130
	s_lshl_b32 s0, s13, 11
	s_and_b32 s0, s0, 0x800
	v_lshl_or_b32 v38, v38, 13, s0
	s_mov_b64 s[4:5], 0
.LBB0_620:
	s_movk_i32 s0, 32
	s_andn2_b64 vcc, exec, s[4:5]
	v_mov_b64_e32 v[40:41], v[128:129]
	s_cbranch_vccnz .LBB0_622
	s_lshl_b32 s1, s13, 11
	s_movk_i32 s0, 32
	v_mov_b32_e32 v38, s1
	v_mov_b64_e32 v[40:41], v[124:125]

.Lp0_loop:
	v_mov_b32_e32 v112, v1
	v_mov_b32_e32 v113, v15
	v_ashrrev_i32_e32 v2, 10, v1
	v_bfe_u32 v17, v1, 7, 13
	v_mov_b64_e32 v[4:5], s[34:35]
	v_and_b32_e32 v6, 0xfffffc00, v2
	v_bfe_u32 v16, v1, 3, 4
	v_mad_u64_u32 v[4:5], s[0:1], v17, s67, v[4:5]
	v_ashrrev_i32_e32 v7, 31, v6
	v_lshl_add_u64 v[4:5], v[6:7], 1, v[4:5]
	v_lshlrev_b32_e32 v2, 7, v16
	v_lshl_add_u64 v[4:5], v[4:5], 0, v[2:3]
	v_and_b32_e32 v2, 56, v15
	v_mov_b32_e32 v23, v3
	v_lshlrev_b32_e32 v22, 1, v2
	v_lshl_add_u64 v[4:5], v[4:5], 0, v[22:23]
	global_load_dwordx4 v[96:99], v[4:5], off
	v_add_u32_e32 v1, s2, v1
	v_add_u32_e32 v15, s3, v15
	v_ashrrev_i32_e32 v2, 10, v1
	v_bfe_u32 v17, v1, 7, 13
	v_mov_b64_e32 v[4:5], s[34:35]
	v_and_b32_e32 v6, 0xfffffc00, v2
	v_bfe_u32 v16, v1, 3, 4
	v_mad_u64_u32 v[4:5], s[0:1], v17, s67, v[4:5]
	v_ashrrev_i32_e32 v7, 31, v6
	v_lshl_add_u64 v[4:5], v[6:7], 1, v[4:5]
	v_lshlrev_b32_e32 v2, 7, v16
	v_lshl_add_u64 v[4:5], v[4:5], 0, v[2:3]
	v_and_b32_e32 v2, 56, v15
	v_mov_b32_e32 v23, v3
	v_lshlrev_b32_e32 v22, 1, v2
	v_lshl_add_u64 v[4:5], v[4:5], 0, v[22:23]
	global_load_dwordx4 v[100:103], v[4:5], off
	v_add_u32_e32 v1, s2, v1
	v_add_u32_e32 v15, s3, v15
	v_ashrrev_i32_e32 v2, 10, v1
	v_bfe_u32 v17, v1, 7, 13
	v_mov_b64_e32 v[4:5], s[34:35]
	v_and_b32_e32 v6, 0xfffffc00, v2
	v_bfe_u32 v16, v1, 3, 4
	v_mad_u64_u32 v[4:5], s[0:1], v17, s67, v[4:5]
	v_ashrrev_i32_e32 v7, 31, v6
	v_lshl_add_u64 v[4:5], v[6:7], 1, v[4:5]
	v_lshlrev_b32_e32 v2, 7, v16
	v_lshl_add_u64 v[4:5], v[4:5], 0, v[2:3]
	v_and_b32_e32 v2, 56, v15
	v_mov_b32_e32 v23, v3
	v_lshlrev_b32_e32 v22, 1, v2
	v_lshl_add_u64 v[4:5], v[4:5], 0, v[22:23]
	global_load_dwordx4 v[104:107], v[4:5], off
	v_add_u32_e32 v1, s2, v1
	v_add_u32_e32 v15, s3, v15
	v_ashrrev_i32_e32 v2, 10, v1
	v_bfe_u32 v17, v1, 7, 13
	v_mov_b64_e32 v[4:5], s[34:35]
	v_and_b32_e32 v6, 0xfffffc00, v2
	v_bfe_u32 v16, v1, 3, 4
	v_mad_u64_u32 v[4:5], s[0:1], v17, s67, v[4:5]
	v_ashrrev_i32_e32 v7, 31, v6
	v_lshl_add_u64 v[4:5], v[6:7], 1, v[4:5]
	v_lshlrev_b32_e32 v2, 7, v16
	v_lshl_add_u64 v[4:5], v[4:5], 0, v[2:3]
	v_and_b32_e32 v2, 56, v15
	v_mov_b32_e32 v23, v3
	v_lshlrev_b32_e32 v22, 1, v2
	v_lshl_add_u64 v[4:5], v[4:5], 0, v[22:23]
	global_load_dwordx4 v[108:111], v[4:5], off
	v_mov_b32_e32 v1, v112
	v_mov_b32_e32 v15, v113
	v_ashrrev_i32_e32 v2, 10, v1
	v_bfe_u32 v17, v1, 7, 13
	v_mov_b64_e32 v[4:5], s[34:35]
	v_and_b32_e32 v6, 0xfffffc00, v2
	v_bfe_u32 v16, v1, 3, 4
	v_mad_u64_u32 v[4:5], s[0:1], v17, s67, v[4:5]
	v_ashrrev_i32_e32 v7, 31, v6
	v_lshl_add_u64 v[4:5], v[6:7], 1, v[4:5]
	v_lshlrev_b32_e32 v2, 7, v16
	v_lshl_add_u64 v[4:5], v[4:5], 0, v[2:3]
	v_cmp_lt_u32_e32 vcc, s15, v1
	v_and_b32_e32 v2, 56, v15
	v_mov_b32_e32 v23, v3
	v_lshlrev_b32_e32 v22, 1, v2
	v_lshl_add_u64 v[4:5], v[4:5], 0, v[22:23]
	s_waitcnt vmcnt(3)
	v_mov_b64_e32 v[4:5], v[96:97]
	v_mov_b64_e32 v[6:7], v[98:99]
	v_lshlrev_b32_e32 v2, 2, v2
	v_mov_b32_e32 v37, 0xe8a0000
	s_movk_i32 s0, 0x1000
	v_cmp_gt_u32_e64 s[0:1], s0, v17
	v_cndmask_b32_e32 v8, v80, v88, vcc
	v_cndmask_b32_e32 v9, v81, v89, vcc
	v_cndmask_b32_e32 v10, v82, v90, vcc
	v_cndmask_b32_e32 v11, v83, v91, vcc
	v_cndmask_b32_e32 v18, v84, v92, vcc
	v_cndmask_b32_e32 v19, v85, v93, vcc
	v_cndmask_b32_e32 v20, v86, v94, vcc
	v_cndmask_b32_e32 v21, v87, v95, vcc
	v_lshlrev_b32_e32 v24, 16, v4
	v_and_b32_e32 v25, 0xffff0000, v4
	v_lshlrev_b32_e32 v4, 16, v5
	v_and_b32_e32 v5, 0xffff0000, v5
	v_pk_mul_f32 v[28:29], v[24:25], v[24:25]
	v_pk_mul_f32 v[30:31], v[4:5], v[4:5]
	v_add_f32_e32 v28, v28, v29
	v_lshlrev_b32_e32 v26, 16, v6
	v_and_b32_e32 v27, 0xffff0000, v6
	v_add_f32_e32 v28, v28, v30
	v_pk_mul_f32 v[32:33], v[26:27], v[26:27]
	v_add_f32_e32 v28, v31, v28
	v_lshlrev_b32_e32 v6, 16, v7
	v_and_b32_e32 v7, 0xffff0000, v7
	v_add_f32_e32 v28, v32, v28
	v_pk_mul_f32 v[34:35], v[6:7], v[6:7]
	v_add_f32_e32 v28, v33, v28
	v_add_f32_e32 v28, v34, v28
	v_add_f32_e32 v28, v35, v28
	ds_bpermute_b32 v30, v12, v28
	v_mov_b32_e32 v29, v3
	v_mov_b32_e32 v31, v3
	v_mov_b32_e32 v33, v3
	v_lshlrev_b32_e32 v32, 7, v17
	s_andn2_b64 s[98:99], vcc, s[0:1]
	v_and_b32_e32 v120, 31, v17
	v_lshlrev_b32_e32 v120, 5, v120
	v_and_b32_e32 v121, 0xffffffe0, v17
	v_lshl_or_b32 v120, v121, 7, v120
	v_bfe_u32 v121, v15, 4, 2
	v_lshl_or_b32 v120, v121, 10, v120
	v_bfe_u32 v121, v15, 3, 1
	v_lshl_or_b32 v120, v121, 4, v120
	v_cndmask_b32_e64 v32, v32, v120, s[98:99]
	s_waitcnt lgkmcnt(0)
	v_add_f32_e32 v28, v28, v30
	ds_bpermute_b32 v34, v13, v28
	v_lshlrev_b32_e32 v30, 20, v16
	v_cndmask_b32_e64 v17, v232, 1.0, vcc
	s_waitcnt lgkmcnt(0)
	v_add_f32_e32 v34, v28, v34
	ds_bpermute_b32 v35, v14, v34
	v_mov_b32_e32 v28, 0xd8a0000
	v_cndmask_b32_e32 v28, v28, v37, vcc
	v_lshl_add_u64 v[28:29], s[28:29], 0, v[28:29]
	v_lshl_add_u64 v[28:29], v[28:29], 0, v[30:31]
	s_waitcnt lgkmcnt(0)
	v_add_f32_e32 v34, v34, v35
	v_fmamk_f32 v34, v34, 0x3c800000, v218
	v_mul_f32_e32 v35, 0x4b800000, v34
	v_cmp_gt_f32_e64 s[4:5], s71, v34
	v_lshl_add_u64 v[28:29], v[28:29], 0, v[32:33]
	v_cndmask_b32_e64 v22, v22, v3, s[98:99]
	v_lshl_add_u64 v[22:23], v[28:29], 0, v[22:23]
	v_cndmask_b32_e64 v34, v34, v35, s[4:5]
	v_rsq_f32_e32 v34, v34
	s_nop 0
	v_mul_f32_e32 v28, 0x45800000, v34
	v_cndmask_b32_e64 v28, v34, v28, s[4:5]
	v_mul_f32_e32 v28, v17, v28
	s_and_b64 s[4:5], vcc, s[0:1]
	v_pk_mul_f32 v[8:9], v[8:9], v[28:29] op_sel_hi:[1,0]
	v_pk_mul_f32 v[10:11], v[10:11], v[28:29] op_sel_hi:[1,0]
	v_pk_mul_f32 v[18:19], v[18:19], v[28:29] op_sel_hi:[1,0]
	v_pk_mul_f32 v[20:21], v[20:21], v[28:29] op_sel_hi:[1,0]
	v_pk_mul_f32 v[8:9], v[8:9], v[24:25]
	v_pk_mul_f32 v[10:11], v[10:11], v[4:5]
	v_pk_mul_f32 v[4:5], v[18:19], v[26:27]
	v_pk_mul_f32 v[6:7], v[20:21], v[6:7]
	v_cvt_pk_bf16_f32 v18, v8, v9
	v_cvt_pk_bf16_f32 v19, v10, v11
	v_cvt_pk_bf16_f32 v20, v4, v5
	v_cvt_pk_bf16_f32 v21, v6, v7
	global_store_dwordx4 v[22:23], v[18:21], off
	s_and_saveexec_b64 s[0:1], s[4:5]
	s_cbranch_execz .Lp0_t0
	v_lshrrev_b32_e32 v17, 7, v1
	v_lshrrev_b32_e32 v18, 11, v1
	v_and_or_b32 v16, v18, s16, v16
	v_lshlrev_b32_e32 v17, 8, v17
	v_perm_b32 v16, v16, v17, s17
	v_mov_b32_e32 v17, v3
	v_lshl_add_u64 v[16:17], s[8:9], 0, v[16:17]
	v_lshl_add_u64 v[16:17], v[16:17], 0, v[2:3]
	global_store_dwordx4 v[16:17], v[8:11], off
	global_store_dwordx4 v[16:17], v[4:7], off offset:16
.Lp0_t0:
	s_or_b64 exec, exec, s[0:1]
	v_add_u32_e32 v1, s2, v1
	v_add_u32_e32 v15, s3, v15
	v_ashrrev_i32_e32 v2, 10, v1
	v_bfe_u32 v17, v1, 7, 13
	v_mov_b64_e32 v[4:5], s[34:35]
	v_and_b32_e32 v6, 0xfffffc00, v2
	v_bfe_u32 v16, v1, 3, 4
	v_mad_u64_u32 v[4:5], s[0:1], v17, s67, v[4:5]
	v_ashrrev_i32_e32 v7, 31, v6
	v_lshl_add_u64 v[4:5], v[6:7], 1, v[4:5]
	v_lshlrev_b32_e32 v2, 7, v16
	v_lshl_add_u64 v[4:5], v[4:5], 0, v[2:3]
	v_cmp_lt_u32_e32 vcc, s15, v1
	v_and_b32_e32 v2, 56, v15
	v_mov_b32_e32 v23, v3
	v_lshlrev_b32_e32 v22, 1, v2
	v_lshl_add_u64 v[4:5], v[4:5], 0, v[22:23]
	s_waitcnt vmcnt(3)
	v_mov_b64_e32 v[4:5], v[100:101]
	v_mov_b64_e32 v[6:7], v[102:103]
	v_lshlrev_b32_e32 v2, 2, v2
	v_mov_b32_e32 v37, 0xe8a0000
	s_movk_i32 s0, 0x1000
	v_cmp_gt_u32_e64 s[0:1], s0, v17
	v_cndmask_b32_e32 v8, v80, v88, vcc
	v_cndmask_b32_e32 v9, v81, v89, vcc
	v_cndmask_b32_e32 v10, v82, v90, vcc
	v_cndmask_b32_e32 v11, v83, v91, vcc
	v_cndmask_b32_e32 v18, v84, v92, vcc
	v_cndmask_b32_e32 v19, v85, v93, vcc
	v_cndmask_b32_e32 v20, v86, v94, vcc
	v_cndmask_b32_e32 v21, v87, v95, vcc
	v_lshlrev_b32_e32 v24, 16, v4
	v_and_b32_e32 v25, 0xffff0000, v4
	v_lshlrev_b32_e32 v4, 16, v5
	v_and_b32_e32 v5, 0xffff0000, v5
	v_pk_mul_f32 v[28:29], v[24:25], v[24:25]
	v_pk_mul_f32 v[30:31], v[4:5], v[4:5]
	v_add_f32_e32 v28, v28, v29
	v_lshlrev_b32_e32 v26, 16, v6
	v_and_b32_e32 v27, 0xffff0000, v6
	v_add_f32_e32 v28, v28, v30
	v_pk_mul_f32 v[32:33], v[26:27], v[26:27]
	v_add_f32_e32 v28, v31, v28
	v_lshlrev_b32_e32 v6, 16, v7
	v_and_b32_e32 v7, 0xffff0000, v7
	v_add_f32_e32 v28, v32, v28
	v_pk_mul_f32 v[34:35], v[6:7], v[6:7]
	v_add_f32_e32 v28, v33, v28
	v_add_f32_e32 v28, v34, v28
	v_add_f32_e32 v28, v35, v28
	ds_bpermute_b32 v30, v12, v28
	v_mov_b32_e32 v29, v3
	v_mov_b32_e32 v31, v3
	v_mov_b32_e32 v33, v3
	v_lshlrev_b32_e32 v32, 7, v17
	s_andn2_b64 s[98:99], vcc, s[0:1]
	v_and_b32_e32 v120, 31, v17
	v_lshlrev_b32_e32 v120, 5, v120
	v_and_b32_e32 v121, 0xffffffe0, v17
	v_lshl_or_b32 v120, v121, 7, v120
	v_bfe_u32 v121, v15, 4, 2
	v_lshl_or_b32 v120, v121, 10, v120
	v_bfe_u32 v121, v15, 3, 1
	v_lshl_or_b32 v120, v121, 4, v120
	v_cndmask_b32_e64 v32, v32, v120, s[98:99]
	s_waitcnt lgkmcnt(0)
	v_add_f32_e32 v28, v28, v30
	ds_bpermute_b32 v34, v13, v28
	v_lshlrev_b32_e32 v30, 20, v16
	v_cndmask_b32_e64 v17, v232, 1.0, vcc
	s_waitcnt lgkmcnt(0)
	v_add_f32_e32 v34, v28, v34
	ds_bpermute_b32 v35, v14, v34
	v_mov_b32_e32 v28, 0xd8a0000
	v_cndmask_b32_e32 v28, v28, v37, vcc
	v_lshl_add_u64 v[28:29], s[28:29], 0, v[28:29]
	v_lshl_add_u64 v[28:29], v[28:29], 0, v[30:31]
	s_waitcnt lgkmcnt(0)
	v_add_f32_e32 v34, v34, v35
	v_fmamk_f32 v34, v34, 0x3c800000, v218
	v_mul_f32_e32 v35, 0x4b800000, v34
	v_cmp_gt_f32_e64 s[4:5], s71, v34
	v_lshl_add_u64 v[28:29], v[28:29], 0, v[32:33]
	v_cndmask_b32_e64 v22, v22, v3, s[98:99]
	v_lshl_add_u64 v[22:23], v[28:29], 0, v[22:23]
	v_cndmask_b32_e64 v34, v34, v35, s[4:5]
	v_rsq_f32_e32 v34, v34
	s_nop 0
	v_mul_f32_e32 v28, 0x45800000, v34
	v_cndmask_b32_e64 v28, v34, v28, s[4:5]
	v_mul_f32_e32 v28, v17, v28
	s_and_b64 s[4:5], vcc, s[0:1]
	v_pk_mul_f32 v[8:9], v[8:9], v[28:29] op_sel_hi:[1,0]
	v_pk_mul_f32 v[10:11], v[10:11], v[28:29] op_sel_hi:[1,0]
	v_pk_mul_f32 v[18:19], v[18:19], v[28:29] op_sel_hi:[1,0]
	v_pk_mul_f32 v[20:21], v[20:21], v[28:29] op_sel_hi:[1,0]
	v_pk_mul_f32 v[8:9], v[8:9], v[24:25]
	v_pk_mul_f32 v[10:11], v[10:11], v[4:5]
	v_pk_mul_f32 v[4:5], v[18:19], v[26:27]
	v_pk_mul_f32 v[6:7], v[20:21], v[6:7]
	v_cvt_pk_bf16_f32 v18, v8, v9
	v_cvt_pk_bf16_f32 v19, v10, v11
	v_cvt_pk_bf16_f32 v20, v4, v5
	v_cvt_pk_bf16_f32 v21, v6, v7
	global_store_dwordx4 v[22:23], v[18:21], off
	s_and_saveexec_b64 s[0:1], s[4:5]
	s_cbranch_execz .Lp0_t1
	v_lshrrev_b32_e32 v17, 7, v1
	v_lshrrev_b32_e32 v18, 11, v1
	v_and_or_b32 v16, v18, s16, v16
	v_lshlrev_b32_e32 v17, 8, v17
	v_perm_b32 v16, v16, v17, s17
	v_mov_b32_e32 v17, v3
	v_lshl_add_u64 v[16:17], s[8:9], 0, v[16:17]
	v_lshl_add_u64 v[16:17], v[16:17], 0, v[2:3]
	global_store_dwordx4 v[16:17], v[8:11], off
	global_store_dwordx4 v[16:17], v[4:7], off offset:16
.Lp0_t1:
	s_or_b64 exec, exec, s[0:1]
	v_add_u32_e32 v1, s2, v1
	v_add_u32_e32 v15, s3, v15
	v_ashrrev_i32_e32 v2, 10, v1
	v_bfe_u32 v17, v1, 7, 13
	v_mov_b64_e32 v[4:5], s[34:35]
	v_and_b32_e32 v6, 0xfffffc00, v2
	v_bfe_u32 v16, v1, 3, 4
	v_mad_u64_u32 v[4:5], s[0:1], v17, s67, v[4:5]
	v_ashrrev_i32_e32 v7, 31, v6
	v_lshl_add_u64 v[4:5], v[6:7], 1, v[4:5]
	v_lshlrev_b32_e32 v2, 7, v16
	v_lshl_add_u64 v[4:5], v[4:5], 0, v[2:3]
	v_cmp_lt_u32_e32 vcc, s15, v1
	v_and_b32_e32 v2, 56, v15
	v_mov_b32_e32 v23, v3
	v_lshlrev_b32_e32 v22, 1, v2
	v_lshl_add_u64 v[4:5], v[4:5], 0, v[22:23]
	s_waitcnt vmcnt(3)
	v_mov_b64_e32 v[4:5], v[104:105]
	v_mov_b64_e32 v[6:7], v[106:107]
	v_lshlrev_b32_e32 v2, 2, v2
	v_mov_b32_e32 v37, 0xe8a0000
	s_movk_i32 s0, 0x1000
	v_cmp_gt_u32_e64 s[0:1], s0, v17
	v_cndmask_b32_e32 v8, v80, v88, vcc
	v_cndmask_b32_e32 v9, v81, v89, vcc
	v_cndmask_b32_e32 v10, v82, v90, vcc
	v_cndmask_b32_e32 v11, v83, v91, vcc
	v_cndmask_b32_e32 v18, v84, v92, vcc
	v_cndmask_b32_e32 v19, v85, v93, vcc
	v_cndmask_b32_e32 v20, v86, v94, vcc
	v_cndmask_b32_e32 v21, v87, v95, vcc
	v_lshlrev_b32_e32 v24, 16, v4
	v_and_b32_e32 v25, 0xffff0000, v4
	v_lshlrev_b32_e32 v4, 16, v5
	v_and_b32_e32 v5, 0xffff0000, v5
	v_pk_mul_f32 v[28:29], v[24:25], v[24:25]
	v_pk_mul_f32 v[30:31], v[4:5], v[4:5]
	v_add_f32_e32 v28, v28, v29
	v_lshlrev_b32_e32 v26, 16, v6
	v_and_b32_e32 v27, 0xffff0000, v6
	v_add_f32_e32 v28, v28, v30
	v_pk_mul_f32 v[32:33], v[26:27], v[26:27]
	v_add_f32_e32 v28, v31, v28
	v_lshlrev_b32_e32 v6, 16, v7
	v_and_b32_e32 v7, 0xffff0000, v7
	v_add_f32_e32 v28, v32, v28
	v_pk_mul_f32 v[34:35], v[6:7], v[6:7]
	v_add_f32_e32 v28, v33, v28
	v_add_f32_e32 v28, v34, v28
	v_add_f32_e32 v28, v35, v28
	ds_bpermute_b32 v30, v12, v28
	v_mov_b32_e32 v29, v3
	v_mov_b32_e32 v31, v3
	v_mov_b32_e32 v33, v3
	v_lshlrev_b32_e32 v32, 7, v17
	s_andn2_b64 s[98:99], vcc, s[0:1]
	v_and_b32_e32 v120, 31, v17
	v_lshlrev_b32_e32 v120, 5, v120
	v_and_b32_e32 v121, 0xffffffe0, v17
	v_lshl_or_b32 v120, v121, 7, v120
	v_bfe_u32 v121, v15, 4, 2
	v_lshl_or_b32 v120, v121, 10, v120
	v_bfe_u32 v121, v15, 3, 1
	v_lshl_or_b32 v120, v121, 4, v120
	v_cndmask_b32_e64 v32, v32, v120, s[98:99]
	s_waitcnt lgkmcnt(0)
	v_add_f32_e32 v28, v28, v30
	ds_bpermute_b32 v34, v13, v28
	v_lshlrev_b32_e32 v30, 20, v16
	v_cndmask_b32_e64 v17, v232, 1.0, vcc
	s_waitcnt lgkmcnt(0)
	v_add_f32_e32 v34, v28, v34
	ds_bpermute_b32 v35, v14, v34
	v_mov_b32_e32 v28, 0xd8a0000
	v_cndmask_b32_e32 v28, v28, v37, vcc
	v_lshl_add_u64 v[28:29], s[28:29], 0, v[28:29]
	v_lshl_add_u64 v[28:29], v[28:29], 0, v[30:31]
	s_waitcnt lgkmcnt(0)
	v_add_f32_e32 v34, v34, v35
	v_fmamk_f32 v34, v34, 0x3c800000, v218
	v_mul_f32_e32 v35, 0x4b800000, v34
	v_cmp_gt_f32_e64 s[4:5], s71, v34
	v_lshl_add_u64 v[28:29], v[28:29], 0, v[32:33]
	v_cndmask_b32_e64 v22, v22, v3, s[98:99]
	v_lshl_add_u64 v[22:23], v[28:29], 0, v[22:23]
	v_cndmask_b32_e64 v34, v34, v35, s[4:5]
	v_rsq_f32_e32 v34, v34
	s_nop 0
	v_mul_f32_e32 v28, 0x45800000, v34
	v_cndmask_b32_e64 v28, v34, v28, s[4:5]
	v_mul_f32_e32 v28, v17, v28
	s_and_b64 s[4:5], vcc, s[0:1]
	v_pk_mul_f32 v[8:9], v[8:9], v[28:29] op_sel_hi:[1,0]
	v_pk_mul_f32 v[10:11], v[10:11], v[28:29] op_sel_hi:[1,0]
	v_pk_mul_f32 v[18:19], v[18:19], v[28:29] op_sel_hi:[1,0]
	v_pk_mul_f32 v[20:21], v[20:21], v[28:29] op_sel_hi:[1,0]
	v_pk_mul_f32 v[8:9], v[8:9], v[24:25]
	v_pk_mul_f32 v[10:11], v[10:11], v[4:5]
	v_pk_mul_f32 v[4:5], v[18:19], v[26:27]
	v_pk_mul_f32 v[6:7], v[20:21], v[6:7]
	v_cvt_pk_bf16_f32 v18, v8, v9
	v_cvt_pk_bf16_f32 v19, v10, v11
	v_cvt_pk_bf16_f32 v20, v4, v5
	v_cvt_pk_bf16_f32 v21, v6, v7
	global_store_dwordx4 v[22:23], v[18:21], off
	s_and_saveexec_b64 s[0:1], s[4:5]
	s_cbranch_execz .Lp0_t2
	v_lshrrev_b32_e32 v17, 7, v1
	v_lshrrev_b32_e32 v18, 11, v1
	v_and_or_b32 v16, v18, s16, v16
	v_lshlrev_b32_e32 v17, 8, v17
	v_perm_b32 v16, v16, v17, s17
	v_mov_b32_e32 v17, v3
	v_lshl_add_u64 v[16:17], s[8:9], 0, v[16:17]
	v_lshl_add_u64 v[16:17], v[16:17], 0, v[2:3]
	global_store_dwordx4 v[16:17], v[8:11], off
	global_store_dwordx4 v[16:17], v[4:7], off offset:16
.Lp0_t2:
	s_or_b64 exec, exec, s[0:1]
	v_add_u32_e32 v1, s2, v1
	v_add_u32_e32 v15, s3, v15
	v_ashrrev_i32_e32 v2, 10, v1
	v_bfe_u32 v17, v1, 7, 13
	v_mov_b64_e32 v[4:5], s[34:35]
	v_and_b32_e32 v6, 0xfffffc00, v2
	v_bfe_u32 v16, v1, 3, 4
	v_mad_u64_u32 v[4:5], s[0:1], v17, s67, v[4:5]
	v_ashrrev_i32_e32 v7, 31, v6
	v_lshl_add_u64 v[4:5], v[6:7], 1, v[4:5]
	v_lshlrev_b32_e32 v2, 7, v16
	v_lshl_add_u64 v[4:5], v[4:5], 0, v[2:3]
	v_cmp_lt_u32_e32 vcc, s15, v1
	v_and_b32_e32 v2, 56, v15
	v_mov_b32_e32 v23, v3
	v_lshlrev_b32_e32 v22, 1, v2
	v_lshl_add_u64 v[4:5], v[4:5], 0, v[22:23]
	s_waitcnt vmcnt(3)
	v_mov_b64_e32 v[4:5], v[108:109]
	v_mov_b64_e32 v[6:7], v[110:111]
	v_lshlrev_b32_e32 v2, 2, v2
	v_mov_b32_e32 v37, 0xe8a0000
	s_movk_i32 s0, 0x1000
	v_cmp_gt_u32_e64 s[0:1], s0, v17
	v_cndmask_b32_e32 v8, v80, v88, vcc
	v_cndmask_b32_e32 v9, v81, v89, vcc
	v_cndmask_b32_e32 v10, v82, v90, vcc
	v_cndmask_b32_e32 v11, v83, v91, vcc
	v_cndmask_b32_e32 v18, v84, v92, vcc
	v_cndmask_b32_e32 v19, v85, v93, vcc
	v_cndmask_b32_e32 v20, v86, v94, vcc
	v_cndmask_b32_e32 v21, v87, v95, vcc
	v_lshlrev_b32_e32 v24, 16, v4
	v_and_b32_e32 v25, 0xffff0000, v4
	v_lshlrev_b32_e32 v4, 16, v5
	v_and_b32_e32 v5, 0xffff0000, v5
	v_pk_mul_f32 v[28:29], v[24:25], v[24:25]
	v_pk_mul_f32 v[30:31], v[4:5], v[4:5]
	v_add_f32_e32 v28, v28, v29
	v_lshlrev_b32_e32 v26, 16, v6
	v_and_b32_e32 v27, 0xffff0000, v6
	v_add_f32_e32 v28, v28, v30
	v_pk_mul_f32 v[32:33], v[26:27], v[26:27]
	v_add_f32_e32 v28, v31, v28
	v_lshlrev_b32_e32 v6, 16, v7
	v_and_b32_e32 v7, 0xffff0000, v7
	v_add_f32_e32 v28, v32, v28
	v_pk_mul_f32 v[34:35], v[6:7], v[6:7]
	v_add_f32_e32 v28, v33, v28
	v_add_f32_e32 v28, v34, v28
	v_add_f32_e32 v28, v35, v28
	ds_bpermute_b32 v30, v12, v28
	v_mov_b32_e32 v29, v3
	v_mov_b32_e32 v31, v3
	v_mov_b32_e32 v33, v3
	v_lshlrev_b32_e32 v32, 7, v17
	s_andn2_b64 s[98:99], vcc, s[0:1]
	v_and_b32_e32 v120, 31, v17
	v_lshlrev_b32_e32 v120, 5, v120
	v_and_b32_e32 v121, 0xffffffe0, v17
	v_lshl_or_b32 v120, v121, 7, v120
	v_bfe_u32 v121, v15, 4, 2
	v_lshl_or_b32 v120, v121, 10, v120
	v_bfe_u32 v121, v15, 3, 1
	v_lshl_or_b32 v120, v121, 4, v120
	v_cndmask_b32_e64 v32, v32, v120, s[98:99]
	s_waitcnt lgkmcnt(0)
	v_add_f32_e32 v28, v28, v30
	ds_bpermute_b32 v34, v13, v28
	v_lshlrev_b32_e32 v30, 20, v16
	v_cndmask_b32_e64 v17, v232, 1.0, vcc
	s_waitcnt lgkmcnt(0)
	v_add_f32_e32 v34, v28, v34
	ds_bpermute_b32 v35, v14, v34
	v_mov_b32_e32 v28, 0xd8a0000
	v_cndmask_b32_e32 v28, v28, v37, vcc
	v_lshl_add_u64 v[28:29], s[28:29], 0, v[28:29]
	v_lshl_add_u64 v[28:29], v[28:29], 0, v[30:31]
	s_waitcnt lgkmcnt(0)
	v_add_f32_e32 v34, v34, v35
	v_fmamk_f32 v34, v34, 0x3c800000, v218
	v_mul_f32_e32 v35, 0x4b800000, v34
	v_cmp_gt_f32_e64 s[4:5], s71, v34
	v_lshl_add_u64 v[28:29], v[28:29], 0, v[32:33]
	v_cndmask_b32_e64 v22, v22, v3, s[98:99]
	v_lshl_add_u64 v[22:23], v[28:29], 0, v[22:23]
	v_cndmask_b32_e64 v34, v34, v35, s[4:5]
	v_rsq_f32_e32 v34, v34
	s_nop 0
	v_mul_f32_e32 v28, 0x45800000, v34
	v_cndmask_b32_e64 v28, v34, v28, s[4:5]
	v_mul_f32_e32 v28, v17, v28
	s_and_b64 s[4:5], vcc, s[0:1]
	v_pk_mul_f32 v[8:9], v[8:9], v[28:29] op_sel_hi:[1,0]
	v_pk_mul_f32 v[10:11], v[10:11], v[28:29] op_sel_hi:[1,0]
	v_pk_mul_f32 v[18:19], v[18:19], v[28:29] op_sel_hi:[1,0]
	v_pk_mul_f32 v[20:21], v[20:21], v[28:29] op_sel_hi:[1,0]
	v_pk_mul_f32 v[8:9], v[8:9], v[24:25]
	v_pk_mul_f32 v[10:11], v[10:11], v[4:5]
	v_pk_mul_f32 v[4:5], v[18:19], v[26:27]
	v_pk_mul_f32 v[6:7], v[20:21], v[6:7]
	v_cvt_pk_bf16_f32 v18, v8, v9
	v_cvt_pk_bf16_f32 v19, v10, v11
	v_cvt_pk_bf16_f32 v20, v4, v5
	v_cvt_pk_bf16_f32 v21, v6, v7
	global_store_dwordx4 v[22:23], v[18:21], off
	s_and_saveexec_b64 s[0:1], s[4:5]
	s_cbranch_execz .Lp0_t3
	v_lshrrev_b32_e32 v17, 7, v1
	v_lshrrev_b32_e32 v18, 11, v1
	v_and_or_b32 v16, v18, s16, v16
	v_lshlrev_b32_e32 v17, 8, v17
	v_perm_b32 v16, v16, v17, s17
	v_mov_b32_e32 v17, v3
	v_lshl_add_u64 v[16:17], s[8:9], 0, v[16:17]
	v_lshl_add_u64 v[16:17], v[16:17], 0, v[2:3]
	global_store_dwordx4 v[16:17], v[8:11], off
	global_store_dwordx4 v[16:17], v[4:7], off offset:16

.LBB0_771:
	v_ashrrev_i32_e32 v2, 10, v1
	v_bfe_u32 v17, v1, 7, 13
	v_mov_b64_e32 v[4:5], s[34:35]
	v_and_b32_e32 v6, 0xfffffc00, v2
	v_bfe_u32 v16, v1, 3, 4
	v_mad_u64_u32 v[4:5], s[0:1], v17, s67, v[4:5]
	v_ashrrev_i32_e32 v7, 31, v6
	v_lshl_add_u64 v[4:5], v[6:7], 1, v[4:5]
	v_lshlrev_b32_e32 v2, 7, v16
	v_lshl_add_u64 v[4:5], v[4:5], 0, v[2:3]
	v_cmp_lt_u32_e32 vcc, s15, v1
	v_mov_b32_e32 v2, 0xa8
	v_mov_b32_e32 v6, 0xb0
	v_cndmask_b32_e32 v2, v2, v6, vcc
	v_lshl_add_u64 v[6:7], s[30:31], 0, v[2:3]
	global_load_dwordx2 v[8:9], v[6:7], off
	v_and_b32_e32 v2, 56, v15
	v_mov_b32_e32 v23, v3
	v_lshlrev_b32_e32 v22, 1, v2
	v_lshl_add_u64 v[4:5], v[4:5], 0, v[22:23]
	global_load_dwordx4 v[4:7], v[4:5], off
	v_lshlrev_b32_e32 v2, 2, v2
	v_mov_b32_e32 v37, 0xe8a0000
	s_movk_i32 s0, 0x1000
	v_cmp_gt_u32_e64 s[0:1], s0, v17
	s_waitcnt vmcnt(0)
	v_lshl_add_u64 v[18:19], v[8:9], 0, v[2:3]
	global_load_dwordx4 v[8:11], v[18:19], off
	s_nop 0
	global_load_dwordx4 v[18:21], v[18:19], off offset:16
	v_lshlrev_b32_e32 v24, 16, v4
	v_and_b32_e32 v25, 0xffff0000, v4
	v_lshlrev_b32_e32 v4, 16, v5
	v_and_b32_e32 v5, 0xffff0000, v5
	v_pk_mul_f32 v[28:29], v[24:25], v[24:25]
	v_pk_mul_f32 v[30:31], v[4:5], v[4:5]
	v_add_f32_e32 v28, v28, v29
	v_lshlrev_b32_e32 v26, 16, v6
	v_and_b32_e32 v27, 0xffff0000, v6
	v_add_f32_e32 v28, v28, v30
	v_pk_mul_f32 v[32:33], v[26:27], v[26:27]
	v_add_f32_e32 v28, v31, v28
	v_lshlrev_b32_e32 v6, 16, v7
	v_and_b32_e32 v7, 0xffff0000, v7
	v_add_f32_e32 v28, v32, v28
	v_pk_mul_f32 v[34:35], v[6:7], v[6:7]
	v_add_f32_e32 v28, v33, v28
	v_add_f32_e32 v28, v34, v28
	v_add_f32_e32 v28, v35, v28
	ds_bpermute_b32 v30, v12, v28
	v_mov_b32_e32 v29, v3
	v_mov_b32_e32 v31, v3
	v_mov_b32_e32 v33, v3
	v_lshlrev_b32_e32 v32, 7, v17
	s_andn2_b64 s[98:99], vcc, s[0:1]
	v_and_b32_e32 v120, 31, v17
	v_lshlrev_b32_e32 v120, 5, v120
	v_and_b32_e32 v121, 0xffffffe0, v17
	v_lshl_or_b32 v120, v121, 7, v120
	v_bfe_u32 v121, v15, 4, 2
	v_lshl_or_b32 v120, v121, 10, v120
	v_bfe_u32 v121, v15, 3, 1
	v_lshl_or_b32 v120, v121, 4, v120
	v_cndmask_b32_e64 v32, v32, v120, s[98:99]
	s_waitcnt lgkmcnt(0)
	v_add_f32_e32 v28, v28, v30
	ds_bpermute_b32 v34, v13, v28
	v_lshlrev_b32_e32 v30, 20, v16
	v_cndmask_b32_e64 v17, v232, 1.0, vcc
	s_waitcnt lgkmcnt(0)
	v_add_f32_e32 v34, v28, v34
	ds_bpermute_b32 v35, v14, v34
	v_mov_b32_e32 v28, 0xd8a0000
	v_cndmask_b32_e32 v28, v28, v37, vcc
	v_lshl_add_u64 v[28:29], s[28:29], 0, v[28:29]
	v_lshl_add_u64 v[28:29], v[28:29], 0, v[30:31]
	s_waitcnt lgkmcnt(0)
	v_add_f32_e32 v34, v34, v35
	v_fmamk_f32 v34, v34, 0x3c800000, v218
	v_mul_f32_e32 v35, 0x4b800000, v34
	v_cmp_gt_f32_e64 s[4:5], s71, v34
	v_lshl_add_u64 v[28:29], v[28:29], 0, v[32:33]
	v_cndmask_b32_e64 v22, v22, v3, s[98:99]
	v_lshl_add_u64 v[22:23], v[28:29], 0, v[22:23]
	v_cndmask_b32_e64 v34, v34, v35, s[4:5]
	v_rsq_f32_e32 v34, v34
	s_nop 0
	v_mul_f32_e32 v28, 0x45800000, v34
	v_cndmask_b32_e64 v28, v34, v28, s[4:5]
	v_mul_f32_e32 v28, v17, v28
	s_and_b64 s[4:5], vcc, s[0:1]
	s_waitcnt vmcnt(1)
	v_pk_mul_f32 v[8:9], v[8:9], v[28:29] op_sel_hi:[1,0]
	v_pk_mul_f32 v[10:11], v[10:11], v[28:29] op_sel_hi:[1,0]
	s_waitcnt vmcnt(0)
	v_pk_mul_f32 v[18:19], v[18:19], v[28:29] op_sel_hi:[1,0]
	v_pk_mul_f32 v[20:21], v[20:21], v[28:29] op_sel_hi:[1,0]
	v_pk_mul_f32 v[8:9], v[8:9], v[24:25]
	v_pk_mul_f32 v[10:11], v[10:11], v[4:5]
	v_pk_mul_f32 v[4:5], v[18:19], v[26:27]
	v_pk_mul_f32 v[6:7], v[20:21], v[6:7]
	v_cvt_pk_bf16_f32 v18, v8, v9
	v_cvt_pk_bf16_f32 v19, v10, v11
	v_cvt_pk_bf16_f32 v20, v4, v5
	v_cvt_pk_bf16_f32 v21, v6, v7
	global_store_dwordx4 v[22:23], v[18:21], off
	s_and_saveexec_b64 s[0:1], s[4:5]
	s_cbranch_execz .LBB0_770
	v_lshrrev_b32_e32 v17, 7, v1
	v_lshrrev_b32_e32 v18, 11, v1
	v_and_or_b32 v16, v18, s16, v16
	v_lshlrev_b32_e32 v17, 8, v17
	v_perm_b32 v16, v16, v17, s17
	v_mov_b32_e32 v17, v3
	v_lshl_add_u64 v[16:17], s[8:9], 0, v[16:17]
	v_lshl_add_u64 v[16:17], v[16:17], 0, v[2:3]
	global_store_dwordx4 v[16:17], v[8:11], off
	global_store_dwordx4 v[16:17], v[4:7], off offset:16
	s_branch .LBB0_770

.LBB0_778:
	v_lshrrev_b32_e32 v120, 9, v1
	v_bfe_u32 v121, v1, 3, 3
	v_lshrrev_b32_e32 v122, 4, v120
	v_lshl_or_b32 v122, v122, 3, v121
	v_and_b32_e32 v120, 15, v120
	v_bfe_u32 v121, v1, 6, 3
	v_lshl_or_b32 v120, v120, 3, v121
	v_and_b32_e32 v121, 7, v1
	v_lshl_or_b32 v120, v120, 3, v121
	v_mov_b32_e32 v2, v122
	v_mov_b32_e32 v4, v120
	v_lshlrev_b32_e32 v2, 3, v2
	v_ashrrev_i32_e32 v5, 31, v4
	v_mov_b64_e32 v[8:9], s[34:35]
	v_mad_i64_i32 v[10:11], s[6:7], v2, s67, v[8:9]
	v_lshlrev_b64 v[6:7], 1, v[4:5]
	v_lshl_add_u64 v[10:11], v[10:11], 0, v[6:7]
	v_add_co_u32_e32 v10, vcc, 0x1000, v10
	v_lshlrev_b64 v[4:5], 14, v[4:5]
	s_nop 0
	v_addc_co_u32_e32 v11, vcc, 0, v11, vcc
	global_load_ushort v12, v[10:11], off
	v_or_b32_e32 v10, 1, v2
	v_mad_i64_i32 v[10:11], s[6:7], v10, s67, v[8:9]
	v_lshl_add_u64 v[10:11], v[10:11], 0, v[6:7]
	v_add_co_u32_e32 v10, vcc, 0x1000, v10
	v_lshl_add_u64 v[4:5], s[54:55], 0, v[4:5]
	s_nop 0
	v_addc_co_u32_e32 v11, vcc, 0, v11, vcc
	global_load_ushort v13, v[10:11], off
	v_or_b32_e32 v10, 2, v2
	v_mad_i64_i32 v[10:11], s[6:7], v10, s67, v[8:9]
	v_lshl_add_u64 v[10:11], v[10:11], 0, v[6:7]
	v_add_co_u32_e32 v10, vcc, 0x1000, v10
	v_add_u32_e32 v1, s2, v1
	s_nop 0
	v_addc_co_u32_e32 v11, vcc, 0, v11, vcc
	global_load_ushort v14, v[10:11], off
	v_or_b32_e32 v10, 3, v2
	v_mad_i64_i32 v[10:11], s[6:7], v10, s67, v[8:9]
	v_lshl_add_u64 v[10:11], v[10:11], 0, v[6:7]
	v_add_co_u32_e32 v10, vcc, 0x1000, v10
	s_nop 1
	v_addc_co_u32_e32 v11, vcc, 0, v11, vcc
	global_load_ushort v15, v[10:11], off
	v_or_b32_e32 v10, 4, v2
	v_mad_i64_i32 v[10:11], s[6:7], v10, s67, v[8:9]
	v_lshl_add_u64 v[10:11], v[10:11], 0, v[6:7]
	v_add_co_u32_e32 v10, vcc, 0x1000, v10
	s_nop 1
	v_addc_co_u32_e32 v11, vcc, 0, v11, vcc
	global_load_ushort v16, v[10:11], off
	v_or_b32_e32 v10, 5, v2
	v_mad_i64_i32 v[10:11], s[6:7], v10, s67, v[8:9]
	v_lshl_add_u64 v[10:11], v[10:11], 0, v[6:7]
	v_add_co_u32_e32 v10, vcc, 0x1000, v10
	s_nop 1
	v_addc_co_u32_e32 v11, vcc, 0, v11, vcc
	global_load_ushort v17, v[10:11], off
	v_or_b32_e32 v10, 6, v2
	v_mad_i64_i32 v[10:11], s[6:7], v10, s67, v[8:9]
	v_lshl_add_u64 v[10:11], v[10:11], 0, v[6:7]
	v_add_co_u32_e32 v10, vcc, 0x1000, v10
	s_nop 1
	v_addc_co_u32_e32 v11, vcc, 0, v11, vcc
	global_load_ushort v10, v[10:11], off
	v_or_b32_e32 v11, 7, v2
	v_mad_i64_i32 v[8:9], s[6:7], v11, s67, v[8:9]
	v_lshl_add_u64 v[6:7], v[8:9], 0, v[6:7]
	v_add_co_u32_e32 v6, vcc, 0x1000, v6
	s_nop 1
	v_addc_co_u32_e32 v7, vcc, 0, v7, vcc
	global_load_ushort v8, v[6:7], off
	v_and_b32_e32 v6, -16, v2
	v_ashrrev_i32_e32 v7, 31, v6
	v_lshl_add_u64 v[4:5], v[6:7], 1, v[4:5]
	v_and_b32_e32 v2, 8, v2
	v_lshl_add_u64 v[4:5], v[4:5], 0, v[2:3]
	v_cmp_lt_i32_e32 vcc, s15, v1
	s_or_b64 s[4:5], vcc, s[4:5]
	v_lshrrev_b32_e32 v123, 6, v120
	v_lshlrev_b32_e32 v123, 20, v123
	v_and_b32_e32 v124, 63, v120
	v_lshl_or_b32 v123, v124, 6, v123
	v_add_u32_e32 v124, 0xfffffe00, v122
	v_lshrrev_b32_e32 v124, 3, v124
	v_lshl_or_b32 v123, v124, 14, v123
	v_bfe_u32 v124, v122, 2, 1
	v_lshl_or_b32 v123, v124, 12, v123
	v_and_b32_e32 v124, 2, v122
	v_lshl_or_b32 v123, v124, 4, v123
	v_and_b32_e32 v124, 1, v122
	v_lshl_or_b32 v123, v124, 3, v123
	v_or_b32_e32 v124, 0x2000, v123
	v_mov_b32_e32 v125, 0
	v_lshl_add_u64 v[124:125], s[54:55], 0, v[124:125]
	v_lshrrev_b32_e32 v126, 9, v122
	v_cmp_ne_u32_e64 s[98:99], 0, v126
	s_nop 1
	v_cndmask_b32_e64 v4, v4, v124, s[98:99]
	v_cndmask_b32_e64 v5, v5, v125, s[98:99]
	s_waitcnt vmcnt(0)
	v_perm_b32 v6, v13, v12, s23
	v_perm_b32 v7, v15, v14, s23
	global_store_dwordx2 v[4:5], v[6:7], off
	v_perm_b32 v6, v17, v16, s23
	v_perm_b32 v7, v8, v10, s23
	global_store_dwordx2 v[4:5], v[6:7], off offset:16
	s_andn2_b64 exec, exec, s[4:5]
	s_cbranch_execnz .LBB0_778
.LBB0_779:
	s_or_b64 exec, exec, s[0:1]
	s_load_dwordx4 s[4:7], s[30:31], 0x10
	s_mov_b32 s0, s87
	v_mov_b32_e32 v1, v0
	s_nop 0
	v_lshl_add_u32 v4, s0, 9, v1
	s_mov_b32 s0, 0x10000
	v_cmp_gt_i32_e32 vcc, s0, v4
	s_and_saveexec_b64 s[0:1], vcc
	s_cbranch_execz .LBB0_782
	s_load_dword s2, s[20:21], 0x0
	v_ashrrev_i32_e32 v5, 31, v4
	v_lshlrev_b64 v[8:9], 5, v[4:5]
	s_waitcnt lgkmcnt(0)
	v_lshl_add_u64 v[8:9], s[4:5], 0, v[8:9]
	v_lshrrev_b32_e32 v120, 8, v4
	v_lshlrev_b32_e32 v120, 12, v120
	v_bfe_u32 v121, v4, 3, 5
	v_lshl_or_b32 v120, v121, 5, v120
	v_bfe_u32 v121, v4, 1, 2
	v_lshl_or_b32 v120, v121, 10, v120
	v_and_b32_e32 v121, 1, v4
	v_lshl_or_b32 v120, v121, 4, v120
	v_mov_b32_e32 v121, 0
	v_lshl_add_u64 v[6:7], s[52:53], 0, v[120:121]
	s_lshl_b32 s4, s2, 9
	s_ashr_i32 s5, s4, 31
	s_lshl_b64 s[8:9], s[4:5], 4
	v_lshl_add_u64 v[8:9], v[8:9], 0, 16
	s_lshl_b64 s[10:11], s[4:5], 5
	s_mov_b64 s[12:13], 0

.LBB0_784:
	v_ashrrev_i32_e32 v2, 31, v1
	v_lshrrev_b32_e32 v2, 21, v2
	v_add_u32_e32 v2, v1, v2
	v_ashrrev_i32_e32 v2, 11, v2
	v_mul_i32_i24_e32 v4, 0x800, v2
	v_sub_u32_e32 v6, v1, v4
	v_ashrrev_i32_e32 v8, 6, v6
	v_ashrrev_i32_e32 v9, 31, v8
	v_lshlrev_b32_e32 v4, 3, v2
	v_and_b32_e32 v2, 63, v6
	v_lshlrev_b64 v[8:9], 16, v[8:9]
	v_lshl_add_u64 v[8:9], s[6:7], 0, v[8:9]
	v_lshlrev_b32_e32 v2, 2, v2
	v_ashrrev_i32_e32 v5, 31, v4
	v_lshl_add_u64 v[8:9], v[8:9], 0, v[2:3]
	v_lshlrev_b64 v[10:11], 8, v[4:5]
	v_lshl_add_u64 v[10:11], v[8:9], 0, v[10:11]
	global_load_dword v2, v[10:11], off
	v_or_b32_e32 v10, 1, v4
	v_ashrrev_i32_e32 v11, 31, v10
	v_lshlrev_b64 v[10:11], 8, v[10:11]
	v_lshl_add_u64 v[10:11], v[8:9], 0, v[10:11]
	global_load_dword v5, v[10:11], off
	v_or_b32_e32 v10, 2, v4
	v_ashrrev_i32_e32 v11, 31, v10
	v_lshlrev_b64 v[10:11], 8, v[10:11]
	v_lshl_add_u64 v[10:11], v[8:9], 0, v[10:11]
	global_load_dword v7, v[10:11], off
	v_or_b32_e32 v10, 3, v4
	v_ashrrev_i32_e32 v11, 31, v10
	v_lshlrev_b64 v[10:11], 8, v[10:11]
	v_lshl_add_u64 v[10:11], v[8:9], 0, v[10:11]
	global_load_dword v12, v[10:11], off
	v_or_b32_e32 v10, 4, v4
	v_ashrrev_i32_e32 v11, 31, v10
	v_lshlrev_b64 v[10:11], 8, v[10:11]
	v_lshl_add_u64 v[10:11], v[8:9], 0, v[10:11]
	global_load_dword v13, v[10:11], off
	v_or_b32_e32 v10, 5, v4
	v_ashrrev_i32_e32 v11, 31, v10
	v_lshlrev_b64 v[10:11], 8, v[10:11]
	v_lshl_add_u64 v[10:11], v[8:9], 0, v[10:11]
	global_load_dword v14, v[10:11], off
	v_or_b32_e32 v10, 6, v4
	v_ashrrev_i32_e32 v11, 31, v10
	v_lshlrev_b64 v[10:11], 8, v[10:11]
	v_lshl_add_u64 v[10:11], v[8:9], 0, v[10:11]
	global_load_dword v15, v[10:11], off
	v_or_b32_e32 v10, 7, v4
	v_ashrrev_i32_e32 v11, 31, v10
	v_lshlrev_b64 v[10:11], 8, v[10:11]
	v_lshl_add_u64 v[8:9], v[8:9], 0, v[10:11]
	global_load_dword v8, v[8:9], off
	v_add_u32_e32 v1, s2, v1
	v_cmp_lt_i32_e32 vcc, s14, v1
	s_or_b64 s[4:5], vcc, s[4:5]
	s_waitcnt vmcnt(0)
	v_bfe_u32 v16, v2, 16, 1
	v_add3_u32 v16, v2, v16, s73
	v_and_b32_e32 v2, 8, v4
	v_bfe_u32 v11, v5, 16, 1
	v_add3_u32 v11, v5, v11, s73
	v_bfe_u32 v10, v7, 16, 1
	v_add3_u32 v10, v7, v10, s73
	v_lshrrev_b32_e32 v120, 6, v6
	v_lshlrev_b32_e32 v120, 15, v120
	v_and_b32_e32 v6, 63, v6
	v_lshl_or_b32 v6, v6, 6, v120
	v_mov_b32_e32 v7, 0
	v_lshl_add_u64 v[6:7], s[40:41], 0, v[6:7]
	v_bfe_u32 v9, v12, 16, 1
	v_add3_u32 v12, v12, v9, s73
	v_bfe_u32 v20, v13, 16, 1
	v_add3_u32 v13, v13, v20, s73
	v_bfe_u32 v19, v14, 16, 1
	v_add3_u32 v14, v14, v19, s73
	v_bfe_u32 v18, v15, 16, 1
	v_add3_u32 v15, v15, v18, s73
	v_bfe_u32 v17, v8, 16, 1
	v_add3_u32 v17, v8, v17, s73
	v_lshrrev_b32_e32 v8, 5, v4
	v_lshlrev_b32_e32 v8, 12, v8
	v_and_b32_e32 v9, 16, v4
	v_lshl_or_b32 v8, v9, 1, v8
	v_mov_b32_e32 v9, 0
	v_lshl_add_u64 v[6:7], v[8:9], 0, v[6:7]
	v_lshl_add_u64 v[4:5], v[6:7], 0, v[2:3]
	v_perm_b32 v7, v12, v10, s18
	v_perm_b32 v6, v11, v16, s18
	global_store_dwordx2 v[4:5], v[6:7], off
	v_perm_b32 v7, v17, v15, s18
	v_perm_b32 v6, v14, v13, s18
	global_store_dwordx2 v[4:5], v[6:7], off offset:16
	s_andn2_b64 exec, exec, s[4:5]
	s_cbranch_execnz .LBB0_784
